# fused P6+P7 with the 8 PSUM loads of a tile issued together before the normalisation steps
# speedup vs baseline: 1.1181x; 1.0056x over previous
; __device__ __forceinline__ void phase7(const Params& p) {
;     ...
;   for (int it = blockIdx.x; it < NX / 4; it += gridDim.x) {
;     int row = it * 4 + wave;
;     float tot = 0.f;
; #pragma unroll
;     for (int j = 0; j < 8; ++j) tot += PSUM[(size_t)j * NX + row];
;     float rs = rsqrtf(tot * (1.f / 1024.f) + 1e-6f);
;     float4* o = (float4*)(p.out + (size_t)row * 1024);
; #pragma unroll
;     for (int i = 0; i < 4; ++i) {
;       float4 v = o[lane + 64 * i]; float4 w = ((const float4*)p.final_w)[lane + 64 * i];
;       v.x *= rs * w.x; v.y *= rs * w.y; v.z *= rs * w.z; v.w *= rs * w.w;
;       o[lane + 64 * i] = v;
;     }
.Lp6_go:
	s_or_b64 exec, exec, s[40:41]
	s_barrier
	v_lshrrev_b32_e32 v182, 4, v218
	v_and_b32_e32 v183, 15, v218
	v_mul_u32_u24_e32 v150, 0x210, v182
	v_lshl_add_u32 v150, v183, 5, v150
	v_add_u32_e32 v150, 16, v150
	v_add_u32_e32 v182, s38, v182
	v_and_b32_e32 v151, 7, v218
	v_lshlrev_b32_e32 v151, 16, v151
	v_lshl_add_u32 v151, v182, 2, v151
	v_mov_b32_e32 v152, v182
	v_ashrrev_i32_e32 v153, 31, v182
	v_lshlrev_b64 v[152:153], 12, v[152:153]
	v_lshl_add_u64 v[152:153], v[4:5], 0, v[152:153]
	s_sub_u32 s63, s20, s2
	s_lshr_b32 s63, s63, 16
	s_lshl_b32 s63, s63, 9
	v_lshl_add_u32 v162, v183, 5, s63
	s_mov_b32 s58, s2
	s_mov_b32 s59, s26
	global_load_dwordx4 v[154:157], v162, s[54:55]
	global_load_dwordx4 v[158:161], v162, s[54:55] offset:16
	v_mov_b32_e32 v165, 0
	global_load_dword v142, v151, s[58:59] offset:0 sc1
	global_load_dword v143, v151, s[58:59] offset:64 sc1
	global_load_dword v144, v151, s[58:59] offset:128 sc1
	global_load_dword v145, v151, s[58:59] offset:192 sc1
	global_load_dword v146, v151, s[58:59] offset:256 sc1
	global_load_dword v147, v151, s[58:59] offset:320 sc1
	global_load_dword v148, v151, s[58:59] offset:384 sc1
	global_load_dword v149, v151, s[58:59] offset:448 sc1
	s_waitcnt vmcnt(0)
	ds_read_b128 v[166:169], v150 offset:0
	ds_read_b128 v[170:173], v150 offset:16
	s_nop 1
	v_add_f32_dpp v142, v142, v142 row_ror:4 row_mask:0xf bank_mask:0xf
	s_nop 1
	v_add_f32_dpp v142, v142, v142 row_ror:2 row_mask:0xf bank_mask:0xf
	s_nop 1
	v_add_f32_dpp v142, v142, v142 row_ror:1 row_mask:0xf bank_mask:0xf
	v_mov_b32_e32 v182, 0x358637bd
	v_fmamk_f32 v142, v142, 0x3a800000, v182
	v_mul_f32_e32 v182, 0x4b800000, v142
	v_cmp_gt_f32_e32 vcc, 0x800000, v142
	s_nop 1
	v_cndmask_b32_e32 v142, v142, v182, vcc
	v_rsq_f32_e32 v142, v142
	s_nop 0
	v_mul_f32_e32 v182, 0x45800000, v142
	v_cndmask_b32_e32 v164, v142, v182, vcc
	v_pk_mul_f32 v[174:175], v[154:155], v[164:165] op_sel_hi:[1,0]
	v_pk_mul_f32 v[176:177], v[156:157], v[164:165] op_sel_hi:[1,0]
	v_pk_mul_f32 v[178:179], v[158:159], v[164:165] op_sel_hi:[1,0]
	v_pk_mul_f32 v[180:181], v[160:161], v[164:165] op_sel_hi:[1,0]
	s_waitcnt lgkmcnt(0)
	v_pk_mul_f32 v[174:175], v[166:167], v[174:175]
	v_pk_mul_f32 v[176:177], v[168:169], v[176:177]
	v_pk_mul_f32 v[178:179], v[170:171], v[178:179]
	v_pk_mul_f32 v[180:181], v[172:173], v[180:181]
	global_store_dwordx4 v[152:153], v[174:177], off
	global_store_dwordx4 v[152:153], v[178:181], off offset:16
	v_lshl_add_u64 v[152:153], v[152:153], 0, s[56:57]
	ds_read_b128 v[166:169], v150 offset:8448
	ds_read_b128 v[170:173], v150 offset:8464
	s_nop 1
	v_add_f32_dpp v143, v143, v143 row_ror:4 row_mask:0xf bank_mask:0xf
	s_nop 1
	v_add_f32_dpp v143, v143, v143 row_ror:2 row_mask:0xf bank_mask:0xf
	s_nop 1
	v_add_f32_dpp v143, v143, v143 row_ror:1 row_mask:0xf bank_mask:0xf
	v_mov_b32_e32 v182, 0x358637bd
	v_fmamk_f32 v143, v143, 0x3a800000, v182
	v_mul_f32_e32 v182, 0x4b800000, v143
	v_cmp_gt_f32_e32 vcc, 0x800000, v143
	s_nop 1
	v_cndmask_b32_e32 v143, v143, v182, vcc
	v_rsq_f32_e32 v143, v143
	s_nop 0
	v_mul_f32_e32 v182, 0x45800000, v143
	v_cndmask_b32_e32 v164, v143, v182, vcc
	v_pk_mul_f32 v[174:175], v[154:155], v[164:165] op_sel_hi:[1,0]
	v_pk_mul_f32 v[176:177], v[156:157], v[164:165] op_sel_hi:[1,0]
	v_pk_mul_f32 v[178:179], v[158:159], v[164:165] op_sel_hi:[1,0]
	v_pk_mul_f32 v[180:181], v[160:161], v[164:165] op_sel_hi:[1,0]
	s_waitcnt lgkmcnt(0)
	v_pk_mul_f32 v[174:175], v[166:167], v[174:175]
	v_pk_mul_f32 v[176:177], v[168:169], v[176:177]
	v_pk_mul_f32 v[178:179], v[170:171], v[178:179]
	v_pk_mul_f32 v[180:181], v[172:173], v[180:181]
	global_store_dwordx4 v[152:153], v[174:177], off
	global_store_dwordx4 v[152:153], v[178:181], off offset:16
	v_lshl_add_u64 v[152:153], v[152:153], 0, s[56:57]
	ds_read_b128 v[166:169], v150 offset:16896
	ds_read_b128 v[170:173], v150 offset:16912
	s_nop 1
	v_add_f32_dpp v144, v144, v144 row_ror:4 row_mask:0xf bank_mask:0xf
	s_nop 1
	v_add_f32_dpp v144, v144, v144 row_ror:2 row_mask:0xf bank_mask:0xf
	s_nop 1
	v_add_f32_dpp v144, v144, v144 row_ror:1 row_mask:0xf bank_mask:0xf
	v_mov_b32_e32 v182, 0x358637bd
	v_fmamk_f32 v144, v144, 0x3a800000, v182
	v_mul_f32_e32 v182, 0x4b800000, v144
	v_cmp_gt_f32_e32 vcc, 0x800000, v144
	s_nop 1
	v_cndmask_b32_e32 v144, v144, v182, vcc
	v_rsq_f32_e32 v144, v144
	s_nop 0
	v_mul_f32_e32 v182, 0x45800000, v144
	v_cndmask_b32_e32 v164, v144, v182, vcc
	v_pk_mul_f32 v[174:175], v[154:155], v[164:165] op_sel_hi:[1,0]
	v_pk_mul_f32 v[176:177], v[156:157], v[164:165] op_sel_hi:[1,0]
	v_pk_mul_f32 v[178:179], v[158:159], v[164:165] op_sel_hi:[1,0]
	v_pk_mul_f32 v[180:181], v[160:161], v[164:165] op_sel_hi:[1,0]
	s_waitcnt lgkmcnt(0)
	v_pk_mul_f32 v[174:175], v[166:167], v[174:175]
	v_pk_mul_f32 v[176:177], v[168:169], v[176:177]
	v_pk_mul_f32 v[178:179], v[170:171], v[178:179]
	v_pk_mul_f32 v[180:181], v[172:173], v[180:181]
	global_store_dwordx4 v[152:153], v[174:177], off
	global_store_dwordx4 v[152:153], v[178:181], off offset:16
	v_lshl_add_u64 v[152:153], v[152:153], 0, s[56:57]
	ds_read_b128 v[166:169], v150 offset:25344
	ds_read_b128 v[170:173], v150 offset:25360
	s_nop 1
	v_add_f32_dpp v145, v145, v145 row_ror:4 row_mask:0xf bank_mask:0xf
	s_nop 1
	v_add_f32_dpp v145, v145, v145 row_ror:2 row_mask:0xf bank_mask:0xf
	s_nop 1
	v_add_f32_dpp v145, v145, v145 row_ror:1 row_mask:0xf bank_mask:0xf
	v_mov_b32_e32 v182, 0x358637bd
	v_fmamk_f32 v145, v145, 0x3a800000, v182
	v_mul_f32_e32 v182, 0x4b800000, v145
	v_cmp_gt_f32_e32 vcc, 0x800000, v145
	s_nop 1
	v_cndmask_b32_e32 v145, v145, v182, vcc
	v_rsq_f32_e32 v145, v145
	s_nop 0
	v_mul_f32_e32 v182, 0x45800000, v145
	v_cndmask_b32_e32 v164, v145, v182, vcc
	v_pk_mul_f32 v[174:175], v[154:155], v[164:165] op_sel_hi:[1,0]
	v_pk_mul_f32 v[176:177], v[156:157], v[164:165] op_sel_hi:[1,0]
	v_pk_mul_f32 v[178:179], v[158:159], v[164:165] op_sel_hi:[1,0]
	v_pk_mul_f32 v[180:181], v[160:161], v[164:165] op_sel_hi:[1,0]
	s_waitcnt lgkmcnt(0)
; __device__ __forceinline__ void phase7(const Params& p) {
;     ...
;   for (int it = blockIdx.x; it < NX / 4; it += gridDim.x) {
;     int row = it * 4 + wave;
;     float tot = 0.f;
; #pragma unroll
;     for (int j = 0; j < 8; ++j) tot += PSUM[(size_t)j * NX + row];
;     float rs = rsqrtf(tot * (1.f / 1024.f) + 1e-6f);
;     float4* o = (float4*)(p.out + (size_t)row * 1024);
; #pragma unroll
;     for (int i = 0; i < 4; ++i) {
;       float4 v = o[lane + 64 * i]; float4 w = ((const float4*)p.final_w)[lane + 64 * i];
;       v.x *= rs * w.x; v.y *= rs * w.y; v.z *= rs * w.z; v.w *= rs * w.w;
;       o[lane + 64 * i] = v;
;     }
	v_pk_mul_f32 v[174:175], v[166:167], v[174:175]
	v_pk_mul_f32 v[176:177], v[168:169], v[176:177]
	v_pk_mul_f32 v[178:179], v[170:171], v[178:179]
	v_pk_mul_f32 v[180:181], v[172:173], v[180:181]
	global_store_dwordx4 v[152:153], v[174:177], off
	global_store_dwordx4 v[152:153], v[178:181], off offset:16
	v_lshl_add_u64 v[152:153], v[152:153], 0, s[56:57]
	ds_read_b128 v[166:169], v150 offset:33792
	ds_read_b128 v[170:173], v150 offset:33808
	s_nop 1
	v_add_f32_dpp v146, v146, v146 row_ror:4 row_mask:0xf bank_mask:0xf
	s_nop 1
	v_add_f32_dpp v146, v146, v146 row_ror:2 row_mask:0xf bank_mask:0xf
	s_nop 1
	v_add_f32_dpp v146, v146, v146 row_ror:1 row_mask:0xf bank_mask:0xf
	v_mov_b32_e32 v182, 0x358637bd
	v_fmamk_f32 v146, v146, 0x3a800000, v182
	v_mul_f32_e32 v182, 0x4b800000, v146
	v_cmp_gt_f32_e32 vcc, 0x800000, v146
	s_nop 1
	v_cndmask_b32_e32 v146, v146, v182, vcc
	v_rsq_f32_e32 v146, v146
	s_nop 0
	v_mul_f32_e32 v182, 0x45800000, v146
	v_cndmask_b32_e32 v164, v146, v182, vcc
	v_pk_mul_f32 v[174:175], v[154:155], v[164:165] op_sel_hi:[1,0]
	v_pk_mul_f32 v[176:177], v[156:157], v[164:165] op_sel_hi:[1,0]
	v_pk_mul_f32 v[178:179], v[158:159], v[164:165] op_sel_hi:[1,0]
	v_pk_mul_f32 v[180:181], v[160:161], v[164:165] op_sel_hi:[1,0]
	s_waitcnt lgkmcnt(0)
	v_pk_mul_f32 v[174:175], v[166:167], v[174:175]
	v_pk_mul_f32 v[176:177], v[168:169], v[176:177]
	v_pk_mul_f32 v[178:179], v[170:171], v[178:179]
	v_pk_mul_f32 v[180:181], v[172:173], v[180:181]
	global_store_dwordx4 v[152:153], v[174:177], off
	global_store_dwordx4 v[152:153], v[178:181], off offset:16
	v_lshl_add_u64 v[152:153], v[152:153], 0, s[56:57]
	ds_read_b128 v[166:169], v150 offset:42240
	ds_read_b128 v[170:173], v150 offset:42256
	s_nop 1
	v_add_f32_dpp v147, v147, v147 row_ror:4 row_mask:0xf bank_mask:0xf
	s_nop 1
	v_add_f32_dpp v147, v147, v147 row_ror:2 row_mask:0xf bank_mask:0xf
	s_nop 1
	v_add_f32_dpp v147, v147, v147 row_ror:1 row_mask:0xf bank_mask:0xf
	v_mov_b32_e32 v182, 0x358637bd
	v_fmamk_f32 v147, v147, 0x3a800000, v182
	v_mul_f32_e32 v182, 0x4b800000, v147
	v_cmp_gt_f32_e32 vcc, 0x800000, v147
	s_nop 1
	v_cndmask_b32_e32 v147, v147, v182, vcc
	v_rsq_f32_e32 v147, v147
	s_nop 0
	v_mul_f32_e32 v182, 0x45800000, v147
	v_cndmask_b32_e32 v164, v147, v182, vcc
	v_pk_mul_f32 v[174:175], v[154:155], v[164:165] op_sel_hi:[1,0]
	v_pk_mul_f32 v[176:177], v[156:157], v[164:165] op_sel_hi:[1,0]
	v_pk_mul_f32 v[178:179], v[158:159], v[164:165] op_sel_hi:[1,0]
	v_pk_mul_f32 v[180:181], v[160:161], v[164:165] op_sel_hi:[1,0]
	s_waitcnt lgkmcnt(0)
	v_pk_mul_f32 v[174:175], v[166:167], v[174:175]
	v_pk_mul_f32 v[176:177], v[168:169], v[176:177]
	v_pk_mul_f32 v[178:179], v[170:171], v[178:179]
	v_pk_mul_f32 v[180:181], v[172:173], v[180:181]
	global_store_dwordx4 v[152:153], v[174:177], off
	global_store_dwordx4 v[152:153], v[178:181], off offset:16
	v_lshl_add_u64 v[152:153], v[152:153], 0, s[56:57]
	ds_read_b128 v[166:169], v150 offset:50688
	ds_read_b128 v[170:173], v150 offset:50704
	s_nop 1
	v_add_f32_dpp v148, v148, v148 row_ror:4 row_mask:0xf bank_mask:0xf
	s_nop 1
	v_add_f32_dpp v148, v148, v148 row_ror:2 row_mask:0xf bank_mask:0xf
	s_nop 1
	v_add_f32_dpp v148, v148, v148 row_ror:1 row_mask:0xf bank_mask:0xf
	v_mov_b32_e32 v182, 0x358637bd
	v_fmamk_f32 v148, v148, 0x3a800000, v182
	v_mul_f32_e32 v182, 0x4b800000, v148
	v_cmp_gt_f32_e32 vcc, 0x800000, v148
	s_nop 1
	v_cndmask_b32_e32 v148, v148, v182, vcc
	v_rsq_f32_e32 v148, v148
	s_nop 0
	v_mul_f32_e32 v182, 0x45800000, v148
	v_cndmask_b32_e32 v164, v148, v182, vcc
	v_pk_mul_f32 v[174:175], v[154:155], v[164:165] op_sel_hi:[1,0]
	v_pk_mul_f32 v[176:177], v[156:157], v[164:165] op_sel_hi:[1,0]
	v_pk_mul_f32 v[178:179], v[158:159], v[164:165] op_sel_hi:[1,0]
	v_pk_mul_f32 v[180:181], v[160:161], v[164:165] op_sel_hi:[1,0]
	s_waitcnt lgkmcnt(0)
	v_pk_mul_f32 v[174:175], v[166:167], v[174:175]
	v_pk_mul_f32 v[176:177], v[168:169], v[176:177]
	v_pk_mul_f32 v[178:179], v[170:171], v[178:179]
	v_pk_mul_f32 v[180:181], v[172:173], v[180:181]
	global_store_dwordx4 v[152:153], v[174:177], off
	global_store_dwordx4 v[152:153], v[178:181], off offset:16
	v_lshl_add_u64 v[152:153], v[152:153], 0, s[56:57]
	ds_read_b128 v[166:169], v150 offset:59136
	ds_read_b128 v[170:173], v150 offset:59152
	s_nop 1
	v_add_f32_dpp v149, v149, v149 row_ror:4 row_mask:0xf bank_mask:0xf
	s_nop 1
	v_add_f32_dpp v149, v149, v149 row_ror:2 row_mask:0xf bank_mask:0xf
	s_nop 1
	v_add_f32_dpp v149, v149, v149 row_ror:1 row_mask:0xf bank_mask:0xf
	v_mov_b32_e32 v182, 0x358637bd
	v_fmamk_f32 v149, v149, 0x3a800000, v182
	v_mul_f32_e32 v182, 0x4b800000, v149
	v_cmp_gt_f32_e32 vcc, 0x800000, v149
	s_nop 1
	v_cndmask_b32_e32 v149, v149, v182, vcc
	v_rsq_f32_e32 v149, v149
	s_nop 0
	v_mul_f32_e32 v182, 0x45800000, v149
	v_cndmask_b32_e32 v164, v149, v182, vcc
	v_pk_mul_f32 v[174:175], v[154:155], v[164:165] op_sel_hi:[1,0]
	v_pk_mul_f32 v[176:177], v[156:157], v[164:165] op_sel_hi:[1,0]
	v_pk_mul_f32 v[178:179], v[158:159], v[164:165] op_sel_hi:[1,0]
	v_pk_mul_f32 v[180:181], v[160:161], v[164:165] op_sel_hi:[1,0]
	s_waitcnt lgkmcnt(0)
	v_pk_mul_f32 v[174:175], v[166:167], v[174:175]
	v_pk_mul_f32 v[176:177], v[168:169], v[176:177]
	v_pk_mul_f32 v[178:179], v[170:171], v[178:179]
	v_pk_mul_f32 v[180:181], v[172:173], v[180:181]
	global_store_dwordx4 v[152:153], v[174:177], off
	global_store_dwordx4 v[152:153], v[178:181], off offset:16
	s_branch .LBB0_426
